# mixer1 prompt units: the wave's four LN rows fetched in one batch instead of one exposed load per row
# speedup vs baseline: 1.0172x; 1.0045x over previous
; __device__ __forceinline__ unsigned pk2(float lo, float hi) { return pg8::cvt_pk_bf16(lo, hi); }
; __device__ __forceinline__ void phase_mixer1(const Params& p, LAS unsigned char* lds) {
;     ...
;             {
;                 const int sub = lane >> 4, c8 = (lane & 15) * 8; float g8[8], b8[8]; load8f(lng + g * 128 + c8, g8); load8f(lnb + g * 128 + c8, b8);
; #pragma unroll
;                 for (int ps = 0; ps < 4; ++ps) {
;                     const int t = 16 * wave + 4 * ps + sub; const float mean = stats[2 * t], rstd = stats[2 * t + 1];
;                     float x[8]; unpack8(*(const v4u*)(Z + (row0 + t) * NZ1 + 1024 + g * 128 + c8), x);
; #pragma unroll
;                     for (int q = 0; q < 8; ++q) { const float vn = (x[q] - mean) * rstd * g8[q] + b8[q]; vnT[vnt_off(c8 + q, t)] = (unsigned short)(pk2(vn, 0.f) & 0xffffu); }
;                 }
;             }
.LBB0_878:
	s_or_b64 exec, exec, s[6:7]
	s_lshr_b32 s6, s78, 7
	s_and_b32 s7, s6, 2
	v_lshl_add_u64 v[2:3], s[0:1], 0, v[118:119]
	v_mov_b64_e32 v[0:1], s[34:35]
	s_add_i32 s7, s7, s78
	v_mad_u64_u32 v[4:5], s[16:17], v2, s65, v[0:1]
	s_and_b32 s28, s7, 3
	v_mov_b32_e32 v2, v5
	s_lshl_b32 s40, s28, 9
	v_mad_u64_u32 v[2:3], s[16:17], v3, s65, v[2:3]
	v_lshl_add_u64 v[6:7], v[92:93], 0, s[40:41]
	v_lshl_add_u64 v[8:9], v[94:95], 0, s[40:41]
	v_mov_b32_e32 v5, v2
	s_lshl_b32 s40, s28, 8
	v_lshl_add_u64 v[2:3], v[4:5], 0, s[40:41]
	v_mov_b32_e32 v139, v79
	v_lshl_add_u64 v[2:3], v[2:3], 0, v[138:139]
	s_waitcnt lgkmcnt(0)
	s_barrier
	global_load_dwordx4 v[2:5], v[2:3], off offset:2048
	s_nop 0
	global_load_dwordx4 v[28:31], v[8:9], off
	global_load_dwordx4 v[36:39], v[6:7], off
	global_load_dwordx4 v[32:35], v[6:7], off offset:16
	global_load_dwordx4 v[24:27], v[8:9], off offset:16
	v_lshl_add_u64 v[242:243], s[0:1], 0, v[120:121]
	v_mad_u64_u32 v[244:245], s[16:17], v242, s65, v[0:1]
	v_mov_b32_e32 v242, v245
	v_mad_u64_u32 v[242:243], s[16:17], v243, s65, v[242:243]
	v_mov_b32_e32 v245, v242
	v_lshl_add_u64 v[242:243], v[244:245], 0, s[40:41]
	v_lshl_add_u64 v[242:243], v[242:243], 0, v[138:139]
	global_load_dwordx4 v[226:229], v[242:243], off offset:2048
	v_lshl_add_u64 v[242:243], s[0:1], 0, v[122:123]
	v_mad_u64_u32 v[244:245], s[16:17], v242, s65, v[0:1]
	v_mov_b32_e32 v242, v245
	v_mad_u64_u32 v[242:243], s[16:17], v243, s65, v[242:243]
	v_mov_b32_e32 v245, v242
	v_lshl_add_u64 v[242:243], v[244:245], 0, s[40:41]
	v_lshl_add_u64 v[242:243], v[242:243], 0, v[138:139]
	global_load_dwordx4 v[230:233], v[242:243], off offset:2048
	v_lshl_add_u64 v[242:243], s[0:1], 0, v[124:125]
	v_mad_u64_u32 v[244:245], s[16:17], v242, s65, v[0:1]
	v_mov_b32_e32 v242, v245
	v_mad_u64_u32 v[242:243], s[16:17], v243, s65, v[242:243]
	v_mov_b32_e32 v245, v242
	v_lshl_add_u64 v[242:243], v[244:245], 0, s[40:41]
	v_lshl_add_u64 v[242:243], v[242:243], 0, v[138:139]
	global_load_dwordx4 v[234:237], v[242:243], off offset:2048
	v_lshl_add_u64 v[8:9], s[0:1], 0, v[120:121]
	ds_read_b64 v[6:7], v197
	v_mad_u64_u32 v[10:11], s[16:17], v8, s65, v[0:1]
	v_mov_b32_e32 v8, v11
	v_mad_u64_u32 v[8:9], s[16:17], v9, s65, v[8:9]
	v_mov_b32_e32 v11, v8
	v_lshl_add_u64 v[8:9], v[10:11], 0, s[40:41]
	v_lshl_add_u64 v[8:9], v[8:9], 0, v[138:139]
	s_andn2_b64 vcc, exec, s[18:19]
	s_waitcnt vmcnt(7)
	v_lshlrev_b32_e32 v10, 16, v2
	v_and_b32_e32 v2, 0xffff0000, v2
	v_lshlrev_b32_e32 v11, 16, v3
	v_and_b32_e32 v3, 0xffff0000, v3
	v_lshlrev_b32_e32 v12, 16, v4
	v_and_b32_e32 v4, 0xffff0000, v4
	v_lshlrev_b32_e32 v13, 16, v5
	v_and_b32_e32 v5, 0xffff0000, v5
	s_waitcnt lgkmcnt(0)
	v_sub_f32_e32 v10, v10, v6
	v_sub_f32_e32 v2, v2, v6
	v_sub_f32_e32 v11, v11, v6
	v_sub_f32_e32 v3, v3, v6
	v_sub_f32_e32 v12, v12, v6
	v_sub_f32_e32 v4, v4, v6
	v_sub_f32_e32 v13, v13, v6
	v_sub_f32_e32 v5, v5, v6
	v_mul_f32_e32 v6, v7, v10
	v_mul_f32_e32 v2, v7, v2
	s_waitcnt vmcnt(5)
	v_fma_f32 v6, v36, v6, v28
	v_fma_f32 v2, v37, v2, v29
	v_mul_f32_e32 v10, v7, v11
	v_cvt_pk_bf16_f32 v6, v6, v79
	ds_write_b16 v147, v6 offset:1024
	v_cvt_pk_bf16_f32 v2, v2, v79
	v_mul_f32_e32 v3, v7, v3
	v_mul_f32_e32 v11, v7, v12
	v_mul_f32_e32 v4, v7, v4
	v_mul_f32_e32 v12, v7, v13
	v_mul_f32_e32 v5, v7, v5
	v_fma_f32 v7, v38, v10, v30
	ds_write_b16 v148, v2 offset:1024
	v_cvt_pk_bf16_f32 v2, v7, v79
	v_fma_f32 v3, v39, v3, v31
	ds_write_b16 v149, v2 offset:1024
	v_cvt_pk_bf16_f32 v2, v3, v79
	s_waitcnt vmcnt(3)
	v_fma_f32 v10, v32, v11, v24
	ds_write_b16 v150, v2 offset:1024
	v_cvt_pk_bf16_f32 v2, v10, v79
	v_fma_f32 v4, v33, v4, v25
	ds_write_b16 v151, v2 offset:1024
	v_cvt_pk_bf16_f32 v2, v4, v79
	v_fma_f32 v11, v34, v12, v26
	v_fma_f32 v5, v35, v5, v27
	ds_write_b16 v152, v2 offset:1024
	v_cvt_pk_bf16_f32 v2, v11, v79
	ds_write_b16 v153, v2 offset:1024
	v_cvt_pk_bf16_f32 v10, v5, v79
	v_lshl_add_u64 v[6:7], s[0:1], 0, v[122:123]
	v_mad_u64_u32 v[8:9], s[16:17], v6, s65, v[0:1]
	v_mov_b32_e32 v6, v9
	v_mad_u64_u32 v[6:7], s[16:17], v7, s65, v[6:7]
	v_mov_b32_e32 v9, v6
	v_lshl_add_u64 v[6:7], v[8:9], 0, s[40:41]
	ds_read_b64 v[8:9], v198
	ds_write_b16 v154, v10 offset:1024
	v_lshl_add_u64 v[6:7], v[6:7], 0, v[138:139]
	s_waitcnt vmcnt(2)
	v_mov_b32_e32 v2, v226
	v_mov_b32_e32 v3, v227
	v_mov_b32_e32 v4, v228
	v_mov_b32_e32 v5, v229
	v_lshlrev_b32_e32 v10, 16, v2
	v_and_b32_e32 v2, 0xffff0000, v2
	v_lshlrev_b32_e32 v11, 16, v3
	v_and_b32_e32 v3, 0xffff0000, v3
	v_lshlrev_b32_e32 v12, 16, v4
	v_and_b32_e32 v4, 0xffff0000, v4
	v_lshlrev_b32_e32 v13, 16, v5
	v_and_b32_e32 v5, 0xffff0000, v5
	s_waitcnt lgkmcnt(1)
	v_sub_f32_e32 v10, v10, v8
	v_sub_f32_e32 v2, v2, v8
	v_sub_f32_e32 v11, v11, v8
	v_sub_f32_e32 v3, v3, v8
	v_sub_f32_e32 v12, v12, v8
	v_sub_f32_e32 v4, v4, v8
	v_sub_f32_e32 v13, v13, v8
	v_sub_f32_e32 v5, v5, v8
	v_mul_f32_e32 v8, v9, v10
	v_mul_f32_e32 v2, v9, v2
	v_fma_f32 v8, v36, v8, v28
	v_fma_f32 v2, v37, v2, v29
	v_mul_f32_e32 v10, v9, v11
	v_cvt_pk_bf16_f32 v8, v8, v79
	ds_write_b16 v155, v8 offset:1024
	v_cvt_pk_bf16_f32 v2, v2, v79
	v_mul_f32_e32 v3, v9, v3
	v_mul_f32_e32 v11, v9, v12
	v_mul_f32_e32 v4, v9, v4
	v_mul_f32_e32 v12, v9, v13
	v_mul_f32_e32 v5, v9, v5
	v_fma_f32 v9, v38, v10, v30
	ds_write_b16 v156, v2 offset:1024
	v_cvt_pk_bf16_f32 v2, v9, v79
	v_fma_f32 v3, v39, v3, v31
	ds_write_b16 v157, v2 offset:1024
	v_cvt_pk_bf16_f32 v2, v3, v79
	v_fma_f32 v10, v32, v11, v24
	ds_write_b16 v158, v2 offset:1024
	v_cvt_pk_bf16_f32 v2, v10, v79
	v_fma_f32 v4, v33, v4, v25
	ds_write_b16 v159, v2 offset:1024
	v_cvt_pk_bf16_f32 v2, v4, v79
	v_fma_f32 v11, v34, v12, v26
	v_fma_f32 v5, v35, v5, v27
	ds_write_b16 v160, v2 offset:1024
	v_cvt_pk_bf16_f32 v2, v11, v79
	ds_write_b16 v161, v2 offset:1024
	v_cvt_pk_bf16_f32 v8, v5, v79
	v_lshl_add_u64 v[6:7], s[0:1], 0, v[124:125]
	v_mad_u64_u32 v[0:1], s[16:17], v6, s65, v[0:1]
	v_mov_b32_e32 v6, v1
	v_mad_u64_u32 v[6:7], s[16:17], v7, s65, v[6:7]
	v_mov_b32_e32 v1, v6
	ds_read_b64 v[6:7], v199
	ds_write_b16 v162, v8 offset:1024
	v_lshl_add_u64 v[0:1], v[0:1], 0, s[40:41]
	v_lshl_add_u64 v[0:1], v[0:1], 0, v[138:139]
	s_waitcnt vmcnt(1)
; __device__ __forceinline__ unsigned pk2(float lo, float hi) { return pg8::cvt_pk_bf16(lo, hi); }
; __device__ __forceinline__ void phase_mixer1(const Params& p, LAS unsigned char* lds) {
;     ...
;                     float x[8]; unpack8(*(const v4u*)(Z + (row0 + t) * NZ1 + 1024 + g * 128 + c8), x);
; #pragma unroll
;                     for (int q = 0; q < 8; ++q) { const float vn = (x[q] - mean) * rstd * g8[q] + b8[q]; vnT[vnt_off(c8 + q, t)] = (unsigned short)(pk2(vn, 0.f) & 0xffffu); }
;                 }
;             }
;             __syncthreads();
;             {
;                 const int fr = lane & 15, fq = lane >> 4, t = 16 * wave + fr;
;                 f32x4 acc[8];
; #pragma unroll
;                 for (int n = 0; n < 8; ++n) acc[n] = (f32x4){0.f, 0.f, 0.f, 0.f};
	v_mov_b32_e32 v2, v230
	v_mov_b32_e32 v3, v231
	v_mov_b32_e32 v4, v232
	v_mov_b32_e32 v5, v233
	v_lshlrev_b32_e32 v8, 16, v2
	v_and_b32_e32 v2, 0xffff0000, v2
	v_lshlrev_b32_e32 v9, 16, v3
	v_and_b32_e32 v3, 0xffff0000, v3
	v_lshlrev_b32_e32 v10, 16, v4
	v_and_b32_e32 v4, 0xffff0000, v4
	v_lshlrev_b32_e32 v11, 16, v5
	v_and_b32_e32 v5, 0xffff0000, v5
	s_waitcnt lgkmcnt(1)
	v_sub_f32_e32 v8, v8, v6
	v_sub_f32_e32 v2, v2, v6
	v_sub_f32_e32 v9, v9, v6
	v_sub_f32_e32 v3, v3, v6
	v_sub_f32_e32 v10, v10, v6
	v_sub_f32_e32 v4, v4, v6
	v_sub_f32_e32 v11, v11, v6
	v_sub_f32_e32 v5, v5, v6
	v_mul_f32_e32 v6, v7, v8
	v_mul_f32_e32 v2, v7, v2
	v_fma_f32 v6, v36, v6, v28
	v_fma_f32 v2, v37, v2, v29
	v_mul_f32_e32 v8, v7, v9
	v_cvt_pk_bf16_f32 v6, v6, v79
	ds_write_b16 v163, v6 offset:1024
	v_cvt_pk_bf16_f32 v2, v2, v79
	v_mul_f32_e32 v3, v7, v3
	v_mul_f32_e32 v9, v7, v10
	v_mul_f32_e32 v4, v7, v4
	v_mul_f32_e32 v10, v7, v11
	v_mul_f32_e32 v5, v7, v5
	v_fma_f32 v7, v38, v8, v30
	ds_write_b16 v164, v2 offset:1024
	v_cvt_pk_bf16_f32 v2, v7, v79
	v_fma_f32 v3, v39, v3, v31
	ds_write_b16 v165, v2 offset:1024
	v_cvt_pk_bf16_f32 v2, v3, v79
	v_fma_f32 v8, v32, v9, v24
	ds_write_b16 v166, v2 offset:1024
	v_cvt_pk_bf16_f32 v2, v8, v79
	v_fma_f32 v4, v33, v4, v25
	ds_write_b16 v167, v2 offset:1024
	v_cvt_pk_bf16_f32 v2, v4, v79
	v_fma_f32 v9, v34, v10, v26
	v_fma_f32 v5, v35, v5, v27
	ds_write_b16 v168, v2 offset:1024
	v_cvt_pk_bf16_f32 v2, v9, v79
	ds_write_b16 v169, v2 offset:1024
	v_cvt_pk_bf16_f32 v44, v5, v79
	ds_read_b64 v[52:53], v200
	ds_write_b16 v170, v44 offset:1024
	v_mov_b32_e32 v3, 0
	v_mov_b32_e32 v2, v3
	v_mov_b32_e32 v1, v3
	v_mov_b32_e32 v0, v3
	v_mov_b32_e32 v7, v3
	v_mov_b32_e32 v6, v3
	v_mov_b32_e32 v5, v3
	v_mov_b32_e32 v4, v3
	v_mov_b32_e32 v11, v3
	v_mov_b32_e32 v10, v3
	v_mov_b32_e32 v9, v3
	v_mov_b32_e32 v8, v3
	v_mov_b32_e32 v15, v3
	v_mov_b32_e32 v14, v3
	v_mov_b32_e32 v13, v3
	v_mov_b32_e32 v12, v3
	v_mov_b32_e32 v19, v3
	v_mov_b32_e32 v18, v3
	v_mov_b32_e32 v17, v3
	v_mov_b32_e32 v16, v3
	v_mov_b32_e32 v23, v3
	v_mov_b32_e32 v22, v3
	v_mov_b32_e32 v21, v3
	v_mov_b32_e32 v20, v3
	v_mov_b32_e32 v43, v3
	v_mov_b32_e32 v42, v3
	v_mov_b32_e32 v41, v3
	v_mov_b32_e32 v40, v3
	v_mov_b32_e32 v47, v3
	v_mov_b32_e32 v46, v3
	v_mov_b32_e32 v45, v3
	s_waitcnt vmcnt(0)
	v_mov_b32_e32 v48, v234
	v_mov_b32_e32 v49, v235
	v_mov_b32_e32 v50, v236
	v_mov_b32_e32 v51, v237
	v_lshlrev_b32_e32 v44, 16, v48
	s_waitcnt lgkmcnt(1)
	v_sub_f32_e32 v44, v44, v52
	v_and_b32_e32 v48, 0xffff0000, v48
	v_mul_f32_e32 v44, v53, v44
	v_lshlrev_b32_e32 v54, 16, v49
	v_lshlrev_b32_e32 v55, 16, v50
	v_sub_f32_e32 v48, v48, v52
	v_fma_f32 v28, v36, v44, v28
	v_and_b32_e32 v49, 0xffff0000, v49
	v_and_b32_e32 v50, 0xffff0000, v50
	v_lshlrev_b32_e32 v56, 16, v51
	v_and_b32_e32 v51, 0xffff0000, v51
	v_sub_f32_e32 v54, v54, v52
	v_sub_f32_e32 v55, v55, v52
	v_mul_f32_e32 v48, v53, v48
	v_cvt_pk_bf16_f32 v28, v28, v79
	v_sub_f32_e32 v49, v49, v52
	v_sub_f32_e32 v50, v50, v52
	v_sub_f32_e32 v56, v56, v52
	v_sub_f32_e32 v51, v51, v52
	v_mul_f32_e32 v52, v53, v54
	v_mul_f32_e32 v54, v53, v55
	v_fma_f32 v29, v37, v48, v29
	ds_write_b16 v171, v28 offset:1024
	v_cvt_pk_bf16_f32 v28, v29, v79
	v_mul_f32_e32 v49, v53, v49
	v_fma_f32 v30, v38, v52, v30
	v_fma_f32 v24, v32, v54, v24
	ds_write_b16 v172, v28 offset:1024
	v_cvt_pk_bf16_f32 v28, v30, v79
	v_mul_f32_e32 v50, v53, v50
	v_fmac_f32_e32 v31, v39, v49
	ds_write_b16 v173, v28 offset:1024
	v_cvt_pk_bf16_f32 v28, v31, v79
	ds_write_b16 v174, v28 offset:1024
	v_cvt_pk_bf16_f32 v24, v24, v79
	v_mul_f32_e32 v55, v53, v56
	v_fma_f32 v25, v33, v50, v25
	ds_write_b16 v175, v24 offset:1024
	v_cvt_pk_bf16_f32 v24, v25, v79
	v_mul_f32_e32 v51, v53, v51
	v_fma_f32 v26, v34, v55, v26
	ds_write_b16 v176, v24 offset:1024
	v_cvt_pk_bf16_f32 v24, v26, v79
	v_mov_b32_e32 v44, v3
	v_fmac_f32_e32 v27, v35, v51
	ds_write_b16 v177, v24 offset:1024
	v_cvt_pk_bf16_f32 v24, v27, v79
	ds_write_b16 v178, v24 offset:1024
	s_waitcnt lgkmcnt(0)
	s_barrier
	s_cbranch_vccnz .LBB0_881
	s_and_b32 s6, s6, 0x1fffffe
	s_add_i32 s6, s6, s77
	s_and_b32 s6, s6, 3
	s_lshl_b32 s40, s6, 15
	v_mov_b32_e32 v44, 0
	v_lshl_add_u64 v[24:25], v[136:137], 0, s[40:41]
	v_mov_b32_e32 v26, v143
	s_mov_b32 s6, s64
	v_mov_b32_e32 v45, v44
	v_mov_b32_e32 v46, v44
	v_mov_b32_e32 v47, v44
	v_mov_b32_e32 v40, v44
	v_mov_b32_e32 v41, v44
	v_mov_b32_e32 v42, v44
	v_mov_b32_e32 v43, v44
	v_mov_b32_e32 v20, v44
	v_mov_b32_e32 v21, v44
	v_mov_b32_e32 v22, v44
	v_mov_b32_e32 v23, v44
	v_mov_b32_e32 v16, v44
	v_mov_b32_e32 v17, v44
	v_mov_b32_e32 v18, v44
	v_mov_b32_e32 v19, v44
	v_mov_b32_e32 v12, v44
	v_mov_b32_e32 v13, v44
	v_mov_b32_e32 v14, v44
	v_mov_b32_e32 v15, v44
	v_mov_b32_e32 v8, v44
	v_mov_b32_e32 v9, v44
	v_mov_b32_e32 v10, v44
	v_mov_b32_e32 v11, v44
	v_mov_b32_e32 v4, v44
	v_mov_b32_e32 v5, v44
	v_mov_b32_e32 v6, v44
	v_mov_b32_e32 v7, v44
	v_mov_b32_e32 v0, v44
	v_mov_b32_e32 v1, v44
	v_mov_b32_e32 v2, v44
	v_mov_b32_e32 v3, v44
